# st1 + diff queue order: all map-0 units (longest first) then all map-1 units, so map-1 never waits on its partner flag
# baseline (speedup 1.0000x reference)
; template <bool NOMAX>
; __device__ __forceinline__ void diff_unit(const AttnCtx& C, int u, LAS unsigned char* lds) {
;     int tid = threadIdx.x; asm volatile("" : "+v"(tid));
;     const int lane = tid & 63, r32 = lane & 31, hi = lane >> 5; const int wid = __builtin_amdgcn_readfirstlane(tid >> 6);
;     const int umap = (u >> 2) & 1, h = u & 3, qb = 63 - (u >> 3);
;     const int n = 4 * qb + 4, q0 = 256 * qb;
;     LAS float* wsf = (LAS float*)(lds + TD_WS) + wid * 64;
;     const LAS float* tab = (const LAS float*)(lds + AL_TAB) + h * 192;
;     const float c15 = tab[0];
;     const int qrel = wid * 32 + r32, qpos = q0 + qrel;
;     const int tmax = n - 4 + (wid >> 1);
;     __syncthreads();
;     const bf16* Qw = C.DQ + (size_t)(q0 + wid * 32) * 512 + h * 128 + umap * 64;
;     const bf16* Kh = C.DK + h * 128 + umap * 64; const bf16* Vh = C.DV + h * 128;
;     const unsigned lds0 = (unsigned)(size_t)lds;
;     const bf16* ksrc = Kh + (size_t)lane * 512 + wid * 8;
;     const bf16* vsrc = Vh + (size_t)(16 * (wid & 3) + (lane >> 2)) * 512 + (wid >> 2) * 32 + (lane & 3) * 8;
;     const unsigned kdst = lds0 + TD_K + wid * 1024, vdst = lds0 + TD_V + wid * 1024;
;     ...
;     const lcp kp0 = (lcp)(lds + TD_K) + hi * 1024 + r32 * 16;
;     const lcp vp0 = (lcp)(lds + TD_V) + ((lane >> 4) & 1) * 32 + (lane & 3) * 8 + (4 * hi + ((lane & 15) >> 2)) * 64;
;     bf16x8 kf[8];
;     DMA_K(0, 0); DMA_V(0, 0); DMA_K(1, SLOTB);
;     const lcp qp0 = (lcp)(lds + TD_Q) + wid * 4096 + lane * 16;
;     {
;         bf16x8 qr[4];
; #pragma unroll
;         for (int d0 = 0; d0 < 4; ++d0) qr[d0] = *(const bf16x8*)(Qw + (size_t)r32 * 512 + d0 * 16 + hi * 8);
; #pragma unroll
;         for (int d0 = 0; d0 < 4; ++d0) *(LAS bf16x8*)((LAS unsigned char*)qp0 + d0 * 1024) = qr[d0];
;     }
;     ...
;     float nm = c15, l_reg = 0.f;
;     f32x16 o[4];
; #pragma unroll
;     for (int d = 0; d < 4; ++d) o[d] = (f32x16){0.f,0.f,0.f,0.f,0.f,0.f,0.f,0.f,0.f,0.f,0.f,0.f,0.f,0.f,0.f,0.f};
;     bool resc = false;
;     ...
;     f32x16 pA0, pA1, pB0, pB1;
;     const f32x16 ZERO16 = (f32x16){0.f,0.f,0.f,0.f,0.f,0.f,0.f,0.f,0.f,0.f,0.f,0.f,0.f,0.f,0.f,0.f};
;     int sl_prev = 0, sl_cur = 0, sl_next = 1;
;     ...
;     DMA_K(2, 2 * SLOTB);
;     TWAIT_BAR(4);
;     {
;         if constexpr (NOMAX) { pA0 = (f32x16){0.f,0.f,0.f,0.f,0.f,0.f,0.f,0.f,0.f,0.f,0.f,0.f,0.f,0.f,0.f,0.f}; pA1 = pA0; } else { INITC(pA0, pA1); }
.LBB0_453:
	s_or_b64 exec, exec, s[2:3]
	s_waitcnt lgkmcnt(0)
	s_barrier
	ds_read_b32 v2, v1
	s_movk_i32 s0, 0x7f
	s_mov_b64 s[2:3], -1
	s_waitcnt lgkmcnt(0)
	v_cmp_lt_u32_e32 vcc, s0, v2
	s_cbranch_vccnz .LBB0_448
	v_readlane_b32 s0, v253, 2
	s_and_b32 s0, s0, 3
	v_and_b32_e32 v254, 63, v2
	v_bfe_u32 v2, v2, 6, 1
	v_lshlrev_b32_e32 v2, 2, v2
	v_lshl_or_b32 v2, v254, 3, v2
	v_or_b32_e32 v2, s0, v2
	v_lshlrev_b32_e32 v4, 1, v2
	v_and_b32_e32 v4, 6, v4
	v_bfe_u32 v230, v2, 2, 1
	v_and_b32_e32 v231, 3, v2
	s_movk_i32 s0, 0x300
	v_or_b32_e32 v4, v4, v230
	v_lshrrev_b32_e32 v7, 3, v2
	v_mul_lo_u32 v2, v231, s0
	v_readlane_b32 s0, v253, 56
	v_lshrrev_b32_e32 v4, v4, v233
	v_lshlrev_b32_e32 v220, 8, v231
	v_mov_b32_e32 v221, v3
	v_readlane_b32 s1, v253, 57
	v_and_b32_e32 v6, 1, v4
	v_add_u32_e32 v2, 0, v2
	v_lshl_add_u64 v[4:5], s[0:1], 0, v[220:221]
	v_readlane_b32 s0, v253, 58
	v_xor_b32_e32 v224, 63, v7
	v_add_u32_e32 v235, 0x20400, v2
	v_lshlrev_b32_e32 v8, 7, v231
	v_lshlrev_b32_e32 v9, 6, v230
	v_lshlrev_b32_e32 v2, 7, v230
	v_readlane_b32 s1, v253, 59
	v_cmp_eq_u32_e32 vcc, 0, v6
	v_lshlrev_b32_e32 v234, 2, v224
	v_lshlrev_b32_e32 v19, 8, v224
	v_lshl_add_u64 v[198:199], v[4:5], 0, v[2:3]
	v_lshl_add_u64 v[196:197], s[0:1], 0, v[220:221]
	v_cmp_ne_u32_e64 s[2:3], 63, v7
	v_lshlrev_b32_e32 v218, 1, v8
	v_lshlrev_b32_e32 v200, 1, v9
	s_cbranch_vccnz .LBB0_465
	v_mov_b32_e32 v6, v0
	v_readlane_b32 s4, v253, 54
	v_readfirstlane_b32 s1, v6
	s_ashr_i32 s6, s1, 6
	s_lshl_b32 s33, s6, 5
	v_add_u32_e32 v202, s33, v19
	v_ashrrev_i32_e32 v203, 31, v202
	v_lshlrev_b64 v[4:5], 10, v[202:203]
	v_readlane_b32 s5, v253, 55
	v_and_b32_e32 v212, 63, v6
	v_mov_b32_e32 v219, v3
	v_lshl_add_u64 v[4:5], s[4:5], 0, v[4:5]
	v_lshl_add_u64 v[4:5], v[4:5], 0, v[218:219]
	v_mov_b32_e32 v201, v3
	v_lshlrev_b32_e32 v2, 10, v212
	s_lshl_b32 s0, s6, 4
	v_bfe_u32 v208, v6, 2, 4
	v_lshl_add_u64 v[8:9], v[4:5], 0, v[200:201]
	v_lshl_add_u64 v[4:5], v[198:199], 0, v[2:3]
	s_lshl_b32 s4, s6, 3
	v_and_or_b32 v2, s0, 48, v208
	s_ashr_i32 s5, s4, 31
	v_lshlrev_b32_e32 v2, 10, v2
	s_ashr_i32 s0, s1, 3
	v_lshl_add_u64 v[204:205], s[4:5], 1, v[4:5]
	v_lshl_add_u64 v[4:5], v[196:197], 0, v[2:3]
	s_and_b32 s4, s0, 0xffffffe0
	v_lshlrev_b32_e32 v2, 3, v6
	s_ashr_i32 s5, s4, 31
	v_and_b32_e32 v7, 24, v2
	s_lshl_b32 s49, s6, 10
	v_and_b32_e32 v210, 31, v6
	ds_read_b32 v213, v235
	s_waitcnt lgkmcnt(0)
	s_barrier
	v_lshl_add_u64 v[4:5], s[4:5], 1, v[4:5]
	v_lshlrev_b32_e32 v2, 1, v7
	s_add_i32 s49, s49, 0
	s_mov_b32 s0, m0
	s_mov_b32 m0, s49
	s_nop 0
	global_load_lds_dwordx4 v[204:205], off
	s_mov_b32 m0, s0
	v_bfe_u32 v211, v6, 5, 1
	v_lshl_add_u64 v[4:5], v[4:5], 0, v[2:3]
	s_add_i32 s58, s49, 0x6000
	s_mov_b32 s0, m0
	s_mov_b32 m0, s58
	s_nop 0
	global_load_lds_dwordx4 v[4:5], off
	s_mov_b32 m0, s0
	v_lshlrev_b32_e32 v2, 10, v210
	v_lshl_add_u64 v[10:11], v[4:5], 0, s[18:19]
	s_add_i32 s0, s49, 0x8000
	s_mov_b32 s7, m0
	s_mov_b32 m0, s0
	s_nop 0
	global_load_lds_dwordx4 v[10:11], off
	s_mov_b32 m0, s7
	v_lshl_add_u64 v[8:9], v[8:9], 0, v[2:3]
	v_lshlrev_b32_e32 v2, 4, v211
	v_lshl_add_u64 v[10:11], v[204:205], 0, s[20:21]
	s_add_i32 s0, s49, 0x2000
	s_mov_b32 s7, m0
	s_mov_b32 m0, s0
	s_nop 0
	global_load_lds_dwordx4 v[10:11], off
	s_mov_b32 m0, s7
	v_lshl_add_u64 v[16:17], v[8:9], 0, v[2:3]
	global_load_dwordx4 v[8:11], v[16:17], off
	global_load_dwordx4 v[12:15], v[16:17], off offset:32
	global_load_dwordx4 v[20:23], v[16:17], off offset:64
	global_load_dwordx4 v[24:27], v[16:17], off offset:96
	s_lshl_b32 s0, s6, 12
	s_add_i32 s7, s0, 0
	v_lshlrev_b32_e32 v16, 4, v212
	s_add_i32 s7, s7, 0x12800
	v_add_u32_e32 v219, s7, v16
	v_lshlrev_b32_e32 v201, 10, v211
	v_lshlrev_b32_e32 v2, 4, v210
	s_add_i32 s8, s49, 0x4000
	v_lshl_add_u64 v[16:17], v[204:205], 0, s[22:23]
	v_add3_u32 v222, 0, v201, v2
	s_ashr_i32 s48, s1, 7
	v_or_b32_e32 v2, s33, v210
	s_and_b64 vcc, exec, s[2:3]
	v_add_u32_e32 v223, s48, v234
	v_add_u32_e32 v215, v2, v19
	s_waitcnt vmcnt(3)
	ds_write_b128 v219, v[8:11]
	s_waitcnt vmcnt(2)
	ds_write_b128 v219, v[12:15] offset:1024
	s_waitcnt vmcnt(1)
	ds_write_b128 v219, v[20:23] offset:2048
	s_waitcnt vmcnt(0)
	ds_write_b128 v219, v[24:27] offset:3072
	s_mov_b32 s7, m0
	s_mov_b32 m0, s8
	s_nop 0
	global_load_lds_dwordx4 v[16:17], off
	s_mov_b32 m0, s7
	s_waitcnt vmcnt(4) lgkmcnt(0)
	s_barrier
	ds_read_b128 v[8:11], v222
	ds_read_b128 v[12:15], v219
	s_waitcnt lgkmcnt(0)
	v_mfma_f32_32x32x16_bf16 v[36:51], v[8:11], v[12:15], 0
	ds_read_b128 v[8:11], v222 offset:512
	s_waitcnt lgkmcnt(0)
	v_mfma_f32_32x32x16_bf16 v[20:35], v[8:11], v[12:15], 0
	ds_read_b128 v[8:11], v222 offset:2048
	ds_read_b128 v[12:15], v219 offset:1024
	s_waitcnt lgkmcnt(0)
	v_mfma_f32_32x32x16_bf16 v[36:51], v[8:11], v[12:15], v[36:51]
	ds_read_b128 v[8:11], v222 offset:2560
	s_waitcnt lgkmcnt(0)
	v_mfma_f32_32x32x16_bf16 v[20:35], v[8:11], v[12:15], v[20:35]
	ds_read_b128 v[8:11], v222 offset:4096
	ds_read_b128 v[12:15], v219 offset:2048
	s_waitcnt lgkmcnt(0)
	v_mfma_f32_32x32x16_bf16 v[36:51], v[8:11], v[12:15], v[36:51]
	ds_read_b128 v[8:11], v222 offset:4608
	s_waitcnt lgkmcnt(0)
	v_mfma_f32_32x32x16_bf16 v[20:35], v[8:11], v[12:15], v[20:35]
	ds_read_b128 v[8:11], v222 offset:6144
	ds_read_b128 v[12:15], v219 offset:3072
	s_waitcnt lgkmcnt(0)
	v_mfma_f32_32x32x16_bf16 v[36:51], v[8:11], v[12:15], v[36:51]
	ds_read_b128 v[8:11], v222 offset:6656
	s_waitcnt lgkmcnt(0)
	v_mfma_f32_32x32x16_bf16 v[20:35], v[8:11], v[12:15], v[20:35]
	s_cbranch_vccnz .LBB0_461
; #define LAS __attribute__((address_space(3)))
; #define TWAIT_BAR(N) asm volatile("s_waitcnt vmcnt(" #N ") lgkmcnt(0)\n\ts_barrier" ::: "memory")
; #define DMA_K(t, slot) glds16(ksrc + (size_t)(t) * 64 * 512, (unsigned)__builtin_amdgcn_readfirstlane(kdst + (slot)))
; #define DMA_K(t, slot) glds16(ksrc + (size_t)(t) * 64 * 512, (unsigned)__builtin_amdgcn_readfirstlane(kdst + (slot)))
; #define INITC(P0, P1) do { _Pragma("unroll") for (int r_ = 0; r_ < 16; ++r_) { P0[r_] = nm; P1[r_] = nm; } } while (0)
; #define INITC(P0, P1) do { _Pragma("unroll") for (int r_ = 0; r_ < 16; ++r_) { P0[r_] = nm; P1[r_] = nm; } } while (0)
; #define NEARK(P0, P1, kk) do { if ((kk) >= 62) _Pragma("unroll") for (int r_ = 0; r_ < 16; ++r_) { const int rel0 = (kk) * 64 + crow(r_, hi) - qpos; int i0 = rel0 < -128 ? -128 : rel0; i0 = i0 > 63 ? 63 : i0; int i1 = rel0 + 32 < -128 ? -128 : rel0 + 32; i1 = i1 > 63 ? 63 : i1; \
;             P0[r_] += tab[i0 + 128] - c15; P1[r_] += tab[i1 + 128] - c15; } } while (0)
; template <bool NOMAX>
; __device__ __forceinline__ void diff_unit(const AttnCtx& C, int u, LAS unsigned char* lds) {
;     ...
;     f32x16 pA0, pA1, pB0, pB1;
;     const f32x16 ZERO16 = (f32x16){0.f,0.f,0.f,0.f,0.f,0.f,0.f,0.f,0.f,0.f,0.f,0.f,0.f,0.f,0.f,0.f};
;     int sl_prev = 0, sl_cur = 0, sl_next = 1;
;     ...
;     DMA_K(2, 2 * SLOTB);
;     TWAIT_BAR(4);
;     {
;         if constexpr (NOMAX) { pA0 = (f32x16){0.f,0.f,0.f,0.f,0.f,0.f,0.f,0.f,0.f,0.f,0.f,0.f,0.f,0.f,0.f,0.f}; pA1 = pA0; } else { INITC(pA0, pA1); }
;         const lcp kb = kp0;
; #pragma unroll
;         for (int d0 = 0; d0 < 4; ++d0) { const bf16x8 b0 = *(const LAS bf16x8*)(kb + d0 * 2048), b1 = *(const LAS bf16x8*)(kb + d0 * 2048 + 512);
;             const bf16x8 qv = QRD(d0); pA0 = __builtin_amdgcn_mfma_f32_32x32x16_bf16(b0, qv, pA0, 0, 0, 0); pA1 = __builtin_amdgcn_mfma_f32_32x32x16_bf16(b1, qv, pA1, 0, 0, 0); }
;         NEARK(pA0, pA1, 0);
	v_cmp_gt_i32_e32 vcc, 0, v223
	v_mov_b32_e32 v2, 0xff800000
	s_and_b64 vcc, exec, vcc
	v_mov_b32_e32 v8, 0xff800000
	v_mov_b32_e32 v9, 0xff800000
	v_mov_b32_e32 v10, 0xff800000
	v_mov_b32_e32 v11, 0xff800000
	v_mov_b32_e32 v12, 0xff800000
	v_mov_b32_e32 v13, 0xff800000
	v_mov_b32_e32 v14, 0xff800000
	v_mov_b32_e32 v15, 0xff800000
	v_mov_b32_e32 v16, 0xff800000
	v_mov_b32_e32 v17, 0xff800000
	v_mov_b32_e32 v52, 0xff800000
	v_mov_b32_e32 v53, 0xff800000
	v_mov_b32_e32 v54, 0xff800000
	v_mov_b32_e32 v55, 0xff800000
	v_mov_b32_e32 v56, 0xff800000
	v_mov_b32_e32 v57, 0xff800000
	v_mov_b32_e32 v58, 0xff800000
	v_mov_b32_e32 v59, 0xff800000
	v_mov_b32_e32 v60, 0xff800000
	v_mov_b32_e32 v61, 0xff800000
	v_mov_b32_e32 v62, 0xff800000
	v_mov_b32_e32 v63, 0xff800000
	v_mov_b32_e32 v64, 0xff800000
	v_mov_b32_e32 v65, 0xff800000
	v_mov_b32_e32 v66, 0xff800000
	v_mov_b32_e32 v67, 0xff800000
	v_mov_b32_e32 v68, 0xff800000
	v_mov_b32_e32 v69, 0xff800000
	v_mov_b32_e32 v70, 0xff800000
	v_mov_b32_e32 v71, 0xff800000
	v_mov_b32_e32 v72, 0xff800000
	s_cbranch_vccnz .LBB0_460
	s_cmp_gt_i32 s6, 5
	s_cbranch_scc1 .LBB0_459
	v_lshlrev_b32_e32 v2, 2, v211
	v_sub_u32_e32 v2, v2, v215
	v_add_u32_e32 v10, 1, v2
	v_add_u32_e32 v12, 2, v2
	v_add_u32_e32 v14, 3, v2
	v_med3_i32 v8, v2, s51, 63
	v_med3_i32 v9, v2, s52, 31
	v_med3_i32 v11, v10, s51, 63
	v_med3_i32 v10, v10, s52, 31
	v_med3_i32 v13, v12, s51, 63
	v_med3_i32 v12, v12, s52, 31
	v_med3_i32 v15, v14, s51, 63
	v_med3_i32 v14, v14, s52, 31
	v_lshl_add_u32 v8, v8, 2, v235
	v_lshl_add_u32 v9, v9, 2, v235
	v_lshl_add_u32 v11, v11, 2, v235
	v_lshl_add_u32 v10, v10, 2, v235
	v_lshl_add_u32 v12, v12, 2, v235
	v_lshl_add_u32 v14, v14, 2, v235
	v_lshl_add_u32 v13, v13, 2, v235
	v_lshl_add_u32 v15, v15, 2, v235
	ds_read_b32 v8, v8 offset:512
	ds_read_b32 v58, v9 offset:640
	ds_read_b32 v9, v11 offset:512
	ds_read_b32 v59, v10 offset:640
	ds_read_b32 v10, v13 offset:512
	ds_read_b32 v60, v12 offset:640
	ds_read_b32 v11, v15 offset:512
	ds_read_b32 v61, v14 offset:640
	v_add_u32_e32 v12, 8, v2
	v_add_u32_e32 v14, 9, v2
	v_add_u32_e32 v16, 10, v2
	v_add_u32_e32 v52, 11, v2
	v_med3_i32 v13, v12, s51, 63
	v_med3_i32 v12, v12, s52, 31
	v_med3_i32 v15, v14, s51, 63
	v_med3_i32 v14, v14, s52, 31
	v_med3_i32 v17, v16, s51, 63
	v_med3_i32 v53, v52, s51, 63
	v_lshl_add_u32 v13, v13, 2, v235
	v_lshl_add_u32 v12, v12, 2, v235
	v_lshl_add_u32 v15, v15, 2, v235
	v_lshl_add_u32 v14, v14, 2, v235
	v_med3_i32 v16, v16, s52, 31
	v_lshl_add_u32 v17, v17, 2, v235
	v_med3_i32 v52, v52, s52, 31
	v_lshl_add_u32 v53, v53, 2, v235
	v_lshl_add_u32 v16, v16, 2, v235
	v_lshl_add_u32 v52, v52, 2, v235
	ds_read_b32 v54, v13 offset:512
	ds_read_b32 v62, v12 offset:640
	ds_read_b32 v12, v15 offset:512
	ds_read_b32 v63, v14 offset:640
	ds_read_b32 v14, v17 offset:512
	ds_read_b32 v64, v16 offset:640
	ds_read_b32 v15, v53 offset:512
	ds_read_b32 v65, v52 offset:640
	v_add_u32_e32 v13, 16, v2
	v_add_u32_e32 v17, 17, v2
	v_add_u32_e32 v53, 18, v2
	v_med3_i32 v16, v13, s51, 63
	v_med3_i32 v13, v13, s52, 31
	v_med3_i32 v52, v17, s51, 63
	v_med3_i32 v55, v53, s51, 63
	v_med3_i32 v53, v53, s52, 31
	v_add_u32_e32 v56, 19, v2
	v_lshl_add_u32 v16, v16, 2, v235
	v_lshl_add_u32 v13, v13, 2, v235
	v_med3_i32 v17, v17, s52, 31
	v_lshl_add_u32 v52, v52, 2, v235
	v_lshl_add_u32 v55, v55, 2, v235
	v_lshl_add_u32 v53, v53, 2, v235
	v_med3_i32 v57, v56, s51, 63
	v_med3_i32 v56, v56, s52, 31
	v_lshl_add_u32 v17, v17, 2, v235
	v_lshl_add_u32 v57, v57, 2, v235
	v_lshl_add_u32 v56, v56, 2, v235
	ds_read_b32 v16, v16 offset:512
	ds_read_b32 v66, v13 offset:640
	ds_read_b32 v52, v52 offset:512
	ds_read_b32 v67, v17 offset:640
	ds_read_b32 v55, v55 offset:512
	ds_read_b32 v68, v53 offset:640
	ds_read_b32 v53, v57 offset:512
	ds_read_b32 v69, v56 offset:640
	v_add_u32_e32 v13, 24, v2
	v_med3_i32 v17, v13, s51, 63
	v_med3_i32 v13, v13, s52, 31
	v_lshl_add_u32 v57, v13, 2, v235
	v_add_u32_e32 v13, 25, v2
	v_lshl_add_u32 v56, v17, 2, v235
	v_med3_i32 v17, v13, s51, 63
	v_med3_i32 v13, v13, s52, 31
	v_lshl_add_u32 v71, v13, 2, v235
	v_add_u32_e32 v13, 26, v2
	v_lshl_add_u32 v70, v17, 2, v235
	v_med3_i32 v17, v13, s51, 63
	v_med3_i32 v13, v13, s52, 31
	v_add_u32_e32 v2, 27, v2
	v_lshl_add_u32 v73, v13, 2, v235
	v_med3_i32 v13, v2, s51, 63
	v_med3_i32 v2, v2, s52, 31
	v_lshl_add_u32 v2, v2, 2, v235
	v_lshl_add_u32 v72, v17, 2, v235
	v_lshl_add_u32 v74, v13, 2, v235
	s_waitcnt lgkmcnt(13)
	v_sub_f32_e32 v13, v12, v213
	v_sub_f32_e32 v12, v54, v213
	s_waitcnt lgkmcnt(5)
	v_sub_f32_e32 v17, v52, v213
	s_waitcnt lgkmcnt(3)
	v_sub_f32_e32 v52, v55, v213
	ds_read_b32 v54, v56 offset:512
	ds_read_b32 v75, v57 offset:640
	ds_read_b32 v55, v70 offset:512
	ds_read_b32 v70, v71 offset:640
	ds_read_b32 v56, v72 offset:512
	ds_read_b32 v57, v74 offset:512
	ds_read_b32 v2, v2 offset:640
	ds_read_b32 v71, v73 offset:640
	v_sub_f32_e32 v8, v8, v213
	v_sub_f32_e32 v9, v9, v213
	v_sub_f32_e32 v11, v11, v213
	v_sub_f32_e32 v10, v10, v213
	v_sub_f32_e32 v15, v15, v213
	v_sub_f32_e32 v14, v14, v213
	v_sub_f32_e32 v16, v16, v213
	s_waitcnt lgkmcnt(9)
	v_sub_f32_e32 v53, v53, v213
	s_waitcnt lgkmcnt(5)
	v_sub_f32_e32 v55, v55, v213
	v_sub_f32_e32 v54, v54, v213
	s_waitcnt lgkmcnt(2)
	v_sub_f32_e32 v57, v57, v213
	v_sub_f32_e32 v56, v56, v213
	v_pk_add_f32 v[50:51], v[50:51], v[56:57]
	v_pk_add_f32 v[48:49], v[48:49], v[54:55]
	v_pk_add_f32 v[46:47], v[46:47], v[52:53]
	v_pk_add_f32 v[44:45], v[44:45], v[16:17]
	v_pk_add_f32 v[42:43], v[42:43], v[14:15]
	v_pk_add_f32 v[40:41], v[40:41], v[12:13]
	v_pk_add_f32 v[38:39], v[38:39], v[10:11]
	v_pk_add_f32 v[36:37], v[36:37], v[8:9]
	v_sub_f32_e32 v8, v58, v213
	v_sub_f32_e32 v9, v59, v213
	v_sub_f32_e32 v11, v61, v213
	v_sub_f32_e32 v10, v60, v213
	v_sub_f32_e32 v13, v63, v213
	v_sub_f32_e32 v12, v62, v213
	v_sub_f32_e32 v15, v65, v213
	v_sub_f32_e32 v14, v64, v213
	v_sub_f32_e32 v17, v67, v213
	v_sub_f32_e32 v16, v66, v213
	v_sub_f32_e32 v53, v69, v213
	v_sub_f32_e32 v52, v68, v213
	v_sub_f32_e32 v55, v70, v213
	v_sub_f32_e32 v54, v75, v213
	s_waitcnt lgkmcnt(1)
	v_sub_f32_e32 v57, v2, v213
	s_waitcnt lgkmcnt(0)
	v_sub_f32_e32 v56, v71, v213
	v_pk_add_f32 v[34:35], v[34:35], v[56:57]
	v_pk_add_f32 v[32:33], v[32:33], v[54:55]
	v_pk_add_f32 v[30:31], v[30:31], v[52:53]
	v_pk_add_f32 v[28:29], v[28:29], v[16:17]
	v_pk_add_f32 v[26:27], v[26:27], v[14:15]
	v_pk_add_f32 v[24:25], v[24:25], v[12:13]
	v_pk_add_f32 v[22:23], v[22:23], v[10:11]
	v_pk_add_f32 v[20:21], v[20:21], v[8:9]
